# hand-scheduled tanh-GELU epilogue (packed f32 math) for the CIN GEMM on top of the fused GU
# speedup vs baseline: 1.0141x; 1.0141x over previous
; __device__ __forceinline__ unsigned cvt_pk_bf16(float lo, float hi) { unsigned r; asm volatile("v_cvt_pk_bf16_f32 %0, %1, %2" : "=v"(r) : "v"(lo), "v"(hi)); return r; }
; __device__ __forceinline__ float gelu_tanh(float x) { const float u = 0.7978845608028654f * (x + 0.044715f * x * x * x); return x * fast_rcp(1.0f + fast_exp2(-2.0f * LOG2E * u)); }
; __device__ __forceinline__ void load_rstd(float (&rsv)[2][4], const ssq_t* ssq, int row0) {
;     ssq_t t[2][4];
; #pragma unroll
;     for (int ai = 0; ai < 2; ++ai)
; #pragma unroll
;         for (int m = 0; m < 4; ++m) t[ai][m] = ssq[row0 + ai * HALF + m * 16];
; #pragma unroll
;     for (int ai = 0; ai < 2; ++ai)
; #pragma unroll
;         for (int m = 0; m < 4; ++m) rsv[ai][m] = __builtin_amdgcn_rsqf((float)t[ai][m] * (SSQ_INV / 1024.0f) + 1e-6f);
; }
;     __device__ __forceinline__ void operator()(const f32x4 (&acc)[2][2][4][2], const Unit& u, int wr, int wc, int fr, int fq) const {
;         const int row0 = u.pm * BM + wr * 64 + fr, col0 = u.pn * BM + wc * 32 + 8 * fq;
;         float rsv[2][4]; load_rstd(rsv, ssq, row0);
; #pragma unroll
;         for (int ai = 0; ai < 2; ++ai)
; #pragma unroll
;             for (int m = 0; m < 4; ++m) { const int row = row0 + ai * HALF + m * 16; bf16_t* rowp = O + (size_t)row * ldc + col0; const float rs = rsv[ai][m];
; #pragma unroll
;                 for (int bj = 0; bj < 2; ++bj) { f32x4 v0 = acc[ai][bj][m][0] * rs, v1 = acc[ai][bj][m][1] * rs;
;                     if (ACT == 1) {
; #pragma unroll
;                         for (int j = 0; j < 4; ++j) { v0[j] = gelu_tanh(v0[j]); v1[j] = gelu_tanh(v1[j]); } }
;                     u32x4 w; w.x = cvt_pk_bf16(v0[0], v0[1]); w.y = cvt_pk_bf16(v0[2], v0[3]); w.z = cvt_pk_bf16(v1[0], v1[1]); w.w = cvt_pk_bf16(v1[2], v1[3]);
;                     *(u32x4*)(rowp + bj * HALF) = w; } }
.LBB0_334:
	v_lshrrev_b32_e32 v152, 8, v170
	v_and_b32_e32 v154, 15, v170
	v_lshl_add_u32 v152, v152, 6, v154
	s_lshl_b32 s10, s64, 8
	v_add_u32_e32 v152, s10, v152
	v_lshlrev_b32_e32 v142, 3, v152
	v_mov_b32_e32 v143, 0
	v_lshl_add_u64 v[142:143], v[142:143], 0, s[26:27]
	global_load_dwordx2 v[144:145], v[142:143], off
	global_load_dwordx2 v[146:147], v[142:143], off offset:128
	global_load_dwordx2 v[148:149], v[142:143], off offset:256
	global_load_dwordx2 v[150:151], v[142:143], off offset:384
	global_load_dwordx2 v[156:157], v[142:143], off offset:1024
	global_load_dwordx2 v[158:159], v[142:143], off offset:1152
	global_load_dwordx2 v[162:163], v[142:143], off offset:1280
	global_load_dwordx2 v[164:165], v[142:143], off offset:1408
	v_bfe_u32 v154, v170, 6, 2
	v_bfe_u32 v160, v170, 4, 2
	v_lshlrev_b32_e32 v154, 5, v154
	v_lshl_or_b32 v154, v160, 3, v154
	s_lshl_b32 s10, s63, 8
	v_add_u32_e32 v154, s10, v154
	v_mul_lo_u32 v152, v152, s28
	v_add_lshl_u32 v160, v152, v154, 1
	v_mov_b32_e32 v166, 0xc038aa3b
	v_mov_b32_e32 v167, 0xc038aa3b
	s_mov_b32 s98, 0x3d372713
	s_mov_b32 s99, 0x3d372713
	s_mov_b32 s100, 0x3f4c422a
	s_mov_b32 s101, 0x3f4c422a
	s_lshl_b32 s10, s28, 5
	s_mov_b32 s11, 0
	s_waitcnt vmcnt(0)
	v_ffbh_u32_e32 v152, v145
	v_min_u32_e32 v152, 32, v152
	v_lshlrev_b64 v[144:145], v152, v[144:145]
	v_min_u32_e32 v144, 1, v144
	v_or_b32_e32 v144, v145, v144
	v_cvt_f32_u32_e32 v144, v144
	v_sub_u32_e32 v152, 32, v152
	v_ldexp_f32 v144, v144, v152
	v_fmamk_f32 v144, v144, 0x30800000, v223
	v_rsq_f32_e32 v144, v144
	v_ffbh_u32_e32 v152, v147
	v_min_u32_e32 v152, 32, v152
	v_lshlrev_b64 v[146:147], v152, v[146:147]
	v_min_u32_e32 v146, 1, v146
	v_or_b32_e32 v146, v147, v146
	v_cvt_f32_u32_e32 v146, v146
	v_sub_u32_e32 v152, 32, v152
	v_ldexp_f32 v146, v146, v152
	v_fmamk_f32 v146, v146, 0x30800000, v223
	v_rsq_f32_e32 v146, v146
	v_ffbh_u32_e32 v152, v149
	v_min_u32_e32 v152, 32, v152
	v_lshlrev_b64 v[148:149], v152, v[148:149]
	v_min_u32_e32 v148, 1, v148
	v_or_b32_e32 v148, v149, v148
	v_cvt_f32_u32_e32 v148, v148
	v_sub_u32_e32 v152, 32, v152
	v_ldexp_f32 v148, v148, v152
	v_fmamk_f32 v148, v148, 0x30800000, v223
	v_rsq_f32_e32 v148, v148
	v_ffbh_u32_e32 v152, v151
	v_min_u32_e32 v152, 32, v152
	v_lshlrev_b64 v[150:151], v152, v[150:151]
	v_min_u32_e32 v150, 1, v150
	v_or_b32_e32 v150, v151, v150
	v_cvt_f32_u32_e32 v150, v150
	v_sub_u32_e32 v152, 32, v152
	v_ldexp_f32 v150, v150, v152
	v_fmamk_f32 v150, v150, 0x30800000, v223
	v_rsq_f32_e32 v150, v150
	v_ffbh_u32_e32 v152, v157
	v_min_u32_e32 v152, 32, v152
	v_lshlrev_b64 v[156:157], v152, v[156:157]
	v_min_u32_e32 v156, 1, v156
	v_or_b32_e32 v156, v157, v156
	v_cvt_f32_u32_e32 v156, v156
	v_sub_u32_e32 v152, 32, v152
	v_ldexp_f32 v156, v156, v152
	v_fmamk_f32 v156, v156, 0x30800000, v223
	v_rsq_f32_e32 v156, v156
	v_ffbh_u32_e32 v152, v159
	v_min_u32_e32 v152, 32, v152
	v_lshlrev_b64 v[158:159], v152, v[158:159]
	v_min_u32_e32 v158, 1, v158
	v_or_b32_e32 v158, v159, v158
	v_cvt_f32_u32_e32 v158, v158
	v_sub_u32_e32 v152, 32, v152
	v_ldexp_f32 v158, v158, v152
	v_fmamk_f32 v158, v158, 0x30800000, v223
	v_rsq_f32_e32 v158, v158
	v_ffbh_u32_e32 v152, v163
	v_min_u32_e32 v152, 32, v152
	v_lshlrev_b64 v[162:163], v152, v[162:163]
	v_min_u32_e32 v162, 1, v162
	v_or_b32_e32 v162, v163, v162
	v_cvt_f32_u32_e32 v162, v162
	v_sub_u32_e32 v152, 32, v152
	v_ldexp_f32 v162, v162, v152
	v_fmamk_f32 v162, v162, 0x30800000, v223
	v_rsq_f32_e32 v162, v162
	v_ffbh_u32_e32 v152, v165
	v_min_u32_e32 v152, 32, v152
	v_lshlrev_b64 v[164:165], v152, v[164:165]
	v_min_u32_e32 v164, 1, v164
	v_or_b32_e32 v164, v165, v164
	v_cvt_f32_u32_e32 v164, v164
	v_sub_u32_e32 v152, 32, v152
	v_ldexp_f32 v164, v164, v152
	v_fmamk_f32 v164, v164, 0x30800000, v223
	v_rsq_f32_e32 v164, v164
	s_nop 1
	v_mov_b32_e32 v165, v164
	v_mov_b32_e32 v164, v162
	v_mov_b32_e32 v163, v158
	v_mov_b32_e32 v162, v156
	v_mov_b32_e32 v159, v150
	v_mov_b32_e32 v158, v148
	v_mov_b32_e32 v157, v146
	v_mov_b32_e32 v156, v144
	v_mov_b32_e32 v142, v160
	v_mov_b32_e32 v143, 0
	v_lshl_add_u64 v[142:143], v[142:143], 0, s[30:31]
	v_pk_mul_f32 v[120:121], v[120:121], v[156:157] op_sel_hi:[1,0]
	v_pk_mul_f32 v[122:123], v[122:123], v[156:157] op_sel_hi:[1,0]
	v_pk_mul_f32 v[124:125], v[124:125], v[156:157] op_sel_hi:[1,0]
	v_pk_mul_f32 v[126:127], v[126:127], v[156:157] op_sel_hi:[1,0]
	v_pk_mul_f32 v[144:145], v[120:121], s[98:99]
	v_pk_mul_f32 v[146:147], v[122:123], s[98:99]
	v_pk_mul_f32 v[148:149], v[124:125], s[98:99]
	v_pk_mul_f32 v[150:151], v[126:127], s[98:99]
	v_pk_mul_f32 v[144:145], v[120:121], v[144:145]
	v_pk_mul_f32 v[146:147], v[122:123], v[146:147]
	v_pk_mul_f32 v[148:149], v[124:125], v[148:149]
	v_pk_mul_f32 v[150:151], v[126:127], v[150:151]
	v_pk_fma_f32 v[144:145], v[120:121], v[144:145], v[120:121]
	v_pk_fma_f32 v[146:147], v[122:123], v[146:147], v[122:123]
	v_pk_fma_f32 v[148:149], v[124:125], v[148:149], v[124:125]
	v_pk_fma_f32 v[150:151], v[126:127], v[150:151], v[126:127]
	v_pk_mul_f32 v[144:145], v[144:145], s[100:101]
	v_pk_mul_f32 v[146:147], v[146:147], s[100:101]
	v_pk_mul_f32 v[148:149], v[148:149], s[100:101]
	v_pk_mul_f32 v[150:151], v[150:151], s[100:101]
	v_pk_mul_f32 v[144:145], v[144:145], v[166:167]
	v_pk_mul_f32 v[146:147], v[146:147], v[166:167]
	v_pk_mul_f32 v[148:149], v[148:149], v[166:167]
	v_pk_mul_f32 v[150:151], v[150:151], v[166:167]
	v_exp_f32_e32 v144, v144
	v_exp_f32_e32 v145, v145
	v_exp_f32_e32 v146, v146
	v_exp_f32_e32 v147, v147
	v_exp_f32_e32 v148, v148
	v_exp_f32_e32 v149, v149
	v_exp_f32_e32 v150, v150
	v_exp_f32_e32 v151, v151
	v_add_f32_e32 v144, 1.0, v144
	v_add_f32_e32 v145, 1.0, v145
; __device__ __forceinline__ unsigned cvt_pk_bf16(float lo, float hi) { unsigned r; asm volatile("v_cvt_pk_bf16_f32 %0, %1, %2" : "=v"(r) : "v"(lo), "v"(hi)); return r; }
; __device__ __forceinline__ float gelu_tanh(float x) { const float u = 0.7978845608028654f * (x + 0.044715f * x * x * x); return x * fast_rcp(1.0f + fast_exp2(-2.0f * LOG2E * u)); }
;     __device__ __forceinline__ void operator()(const f32x4 (&acc)[2][2][4][2], const Unit& u, int wr, int wc, int fr, int fq) const {
;     ...
;             for (int m = 0; m < 4; ++m) { const int row = row0 + ai * HALF + m * 16; bf16_t* rowp = O + (size_t)row * ldc + col0; const float rs = rsv[ai][m];
; #pragma unroll
;                 for (int bj = 0; bj < 2; ++bj) { f32x4 v0 = acc[ai][bj][m][0] * rs, v1 = acc[ai][bj][m][1] * rs;
;                     if (ACT == 1) {
; #pragma unroll
;                         for (int j = 0; j < 4; ++j) { v0[j] = gelu_tanh(v0[j]); v1[j] = gelu_tanh(v1[j]); } }
;                     u32x4 w; w.x = cvt_pk_bf16(v0[0], v0[1]); w.y = cvt_pk_bf16(v0[2], v0[3]); w.z = cvt_pk_bf16(v1[0], v1[1]); w.w = cvt_pk_bf16(v1[2], v1[3]);
;                     *(u32x4*)(rowp + bj * HALF) = w; } }
	v_add_f32_e32 v146, 1.0, v146
	v_add_f32_e32 v147, 1.0, v147
	v_add_f32_e32 v148, 1.0, v148
	v_add_f32_e32 v149, 1.0, v149
	v_add_f32_e32 v150, 1.0, v150
	v_add_f32_e32 v151, 1.0, v151
	v_rcp_f32_e32 v144, v144
	v_rcp_f32_e32 v145, v145
	v_rcp_f32_e32 v146, v146
	v_rcp_f32_e32 v147, v147
	v_rcp_f32_e32 v148, v148
	v_rcp_f32_e32 v149, v149
	v_rcp_f32_e32 v150, v150
	v_rcp_f32_e32 v151, v151
	v_nop
	v_pk_mul_f32 v[120:121], v[120:121], v[144:145]
	v_pk_mul_f32 v[122:123], v[122:123], v[146:147]
	v_pk_mul_f32 v[124:125], v[124:125], v[148:149]
	v_pk_mul_f32 v[126:127], v[126:127], v[150:151]
	v_cvt_pk_bf16_f32 v120, v120, v121
	v_cvt_pk_bf16_f32 v121, v122, v123
	v_cvt_pk_bf16_f32 v122, v124, v125
	v_cvt_pk_bf16_f32 v123, v126, v127
	global_store_dwordx4 v[142:143], v[120:123], off
	v_pk_mul_f32 v[116:117], v[116:117], v[156:157] op_sel_hi:[1,0]
	v_pk_mul_f32 v[118:119], v[118:119], v[156:157] op_sel_hi:[1,0]
	v_pk_mul_f32 v[112:113], v[112:113], v[156:157] op_sel_hi:[1,0]
	v_pk_mul_f32 v[114:115], v[114:115], v[156:157] op_sel_hi:[1,0]
	v_pk_mul_f32 v[144:145], v[116:117], s[98:99]
	v_pk_mul_f32 v[146:147], v[118:119], s[98:99]
	v_pk_mul_f32 v[148:149], v[112:113], s[98:99]
	v_pk_mul_f32 v[150:151], v[114:115], s[98:99]
	v_pk_mul_f32 v[144:145], v[116:117], v[144:145]
	v_pk_mul_f32 v[146:147], v[118:119], v[146:147]
	v_pk_mul_f32 v[148:149], v[112:113], v[148:149]
	v_pk_mul_f32 v[150:151], v[114:115], v[150:151]
	v_pk_fma_f32 v[144:145], v[116:117], v[144:145], v[116:117]
	v_pk_fma_f32 v[146:147], v[118:119], v[146:147], v[118:119]
	v_pk_fma_f32 v[148:149], v[112:113], v[148:149], v[112:113]
	v_pk_fma_f32 v[150:151], v[114:115], v[150:151], v[114:115]
	v_pk_mul_f32 v[144:145], v[144:145], s[100:101]
	v_pk_mul_f32 v[146:147], v[146:147], s[100:101]
	v_pk_mul_f32 v[148:149], v[148:149], s[100:101]
	v_pk_mul_f32 v[150:151], v[150:151], s[100:101]
	v_pk_mul_f32 v[144:145], v[144:145], v[166:167]
	v_pk_mul_f32 v[146:147], v[146:147], v[166:167]
	v_pk_mul_f32 v[148:149], v[148:149], v[166:167]
	v_pk_mul_f32 v[150:151], v[150:151], v[166:167]
	v_exp_f32_e32 v144, v144
	v_exp_f32_e32 v145, v145
	v_exp_f32_e32 v146, v146
	v_exp_f32_e32 v147, v147
	v_exp_f32_e32 v148, v148
	v_exp_f32_e32 v149, v149
	v_exp_f32_e32 v150, v150
	v_exp_f32_e32 v151, v151
	v_add_f32_e32 v144, 1.0, v144
	v_add_f32_e32 v145, 1.0, v145
	v_add_f32_e32 v146, 1.0, v146
	v_add_f32_e32 v147, 1.0, v147
	v_add_f32_e32 v148, 1.0, v148
	v_add_f32_e32 v149, 1.0, v149
	v_add_f32_e32 v150, 1.0, v150
	v_add_f32_e32 v151, 1.0, v151
	v_rcp_f32_e32 v144, v144
	v_rcp_f32_e32 v145, v145
	v_rcp_f32_e32 v146, v146
	v_rcp_f32_e32 v147, v147
	v_rcp_f32_e32 v148, v148
	v_rcp_f32_e32 v149, v149
	v_rcp_f32_e32 v150, v150
	v_rcp_f32_e32 v151, v151
	v_nop
	v_pk_mul_f32 v[116:117], v[116:117], v[144:145]
	v_pk_mul_f32 v[118:119], v[118:119], v[146:147]
	v_pk_mul_f32 v[112:113], v[112:113], v[148:149]
	v_pk_mul_f32 v[114:115], v[114:115], v[150:151]
	v_cvt_pk_bf16_f32 v116, v116, v117
	v_cvt_pk_bf16_f32 v117, v118, v119
	v_cvt_pk_bf16_f32 v118, v112, v113
	v_cvt_pk_bf16_f32 v119, v114, v115
	global_store_dwordx4 v[142:143], v[116:119], off offset:256
	v_lshl_add_u64 v[142:143], v[142:143], 0, s[10:11]
	v_pk_mul_f32 v[108:109], v[108:109], v[156:157] op_sel:[0,1]
	v_pk_mul_f32 v[110:111], v[110:111], v[156:157] op_sel:[0,1]
	v_pk_mul_f32 v[104:105], v[104:105], v[156:157] op_sel:[0,1]
	v_pk_mul_f32 v[106:107], v[106:107], v[156:157] op_sel:[0,1]
	v_pk_mul_f32 v[144:145], v[108:109], s[98:99]
	v_pk_mul_f32 v[146:147], v[110:111], s[98:99]
	v_pk_mul_f32 v[148:149], v[104:105], s[98:99]
	v_pk_mul_f32 v[150:151], v[106:107], s[98:99]
	v_pk_mul_f32 v[144:145], v[108:109], v[144:145]
	v_pk_mul_f32 v[146:147], v[110:111], v[146:147]
	v_pk_mul_f32 v[148:149], v[104:105], v[148:149]
	v_pk_mul_f32 v[150:151], v[106:107], v[150:151]
	v_pk_fma_f32 v[144:145], v[108:109], v[144:145], v[108:109]
	v_pk_fma_f32 v[146:147], v[110:111], v[146:147], v[110:111]
	v_pk_fma_f32 v[148:149], v[104:105], v[148:149], v[104:105]
	v_pk_fma_f32 v[150:151], v[106:107], v[150:151], v[106:107]
	v_pk_mul_f32 v[144:145], v[144:145], s[100:101]
	v_pk_mul_f32 v[146:147], v[146:147], s[100:101]
	v_pk_mul_f32 v[148:149], v[148:149], s[100:101]
	v_pk_mul_f32 v[150:151], v[150:151], s[100:101]
	v_pk_mul_f32 v[144:145], v[144:145], v[166:167]
	v_pk_mul_f32 v[146:147], v[146:147], v[166:167]
	v_pk_mul_f32 v[148:149], v[148:149], v[166:167]
	v_pk_mul_f32 v[150:151], v[150:151], v[166:167]
	v_exp_f32_e32 v144, v144
	v_exp_f32_e32 v145, v145
	v_exp_f32_e32 v146, v146
	v_exp_f32_e32 v147, v147
	v_exp_f32_e32 v148, v148
	v_exp_f32_e32 v149, v149
	v_exp_f32_e32 v150, v150
	v_exp_f32_e32 v151, v151
	v_add_f32_e32 v144, 1.0, v144
	v_add_f32_e32 v145, 1.0, v145
	v_add_f32_e32 v146, 1.0, v146
	v_add_f32_e32 v147, 1.0, v147
	v_add_f32_e32 v148, 1.0, v148
	v_add_f32_e32 v149, 1.0, v149
	v_add_f32_e32 v150, 1.0, v150
	v_add_f32_e32 v151, 1.0, v151
	v_rcp_f32_e32 v144, v144
	v_rcp_f32_e32 v145, v145
	v_rcp_f32_e32 v146, v146
	v_rcp_f32_e32 v147, v147
	v_rcp_f32_e32 v148, v148
	v_rcp_f32_e32 v149, v149
	v_rcp_f32_e32 v150, v150
	v_rcp_f32_e32 v151, v151
	v_nop
	v_pk_mul_f32 v[108:109], v[108:109], v[144:145]
	v_pk_mul_f32 v[110:111], v[110:111], v[146:147]
	v_pk_mul_f32 v[104:105], v[104:105], v[148:149]
	v_pk_mul_f32 v[106:107], v[106:107], v[150:151]
	v_cvt_pk_bf16_f32 v108, v108, v109
	v_cvt_pk_bf16_f32 v109, v110, v111
	v_cvt_pk_bf16_f32 v110, v104, v105
	v_cvt_pk_bf16_f32 v111, v106, v107
	global_store_dwordx4 v[142:143], v[108:111], off
	v_pk_mul_f32 v[100:101], v[100:101], v[156:157] op_sel:[0,1]
	v_pk_mul_f32 v[102:103], v[102:103], v[156:157] op_sel:[0,1]
; __device__ __forceinline__ unsigned cvt_pk_bf16(float lo, float hi) { unsigned r; asm volatile("v_cvt_pk_bf16_f32 %0, %1, %2" : "=v"(r) : "v"(lo), "v"(hi)); return r; }
; __device__ __forceinline__ float gelu_tanh(float x) { const float u = 0.7978845608028654f * (x + 0.044715f * x * x * x); return x * fast_rcp(1.0f + fast_exp2(-2.0f * LOG2E * u)); }
;     __device__ __forceinline__ void operator()(const f32x4 (&acc)[2][2][4][2], const Unit& u, int wr, int wc, int fr, int fq) const {
;     ...
;             for (int m = 0; m < 4; ++m) { const int row = row0 + ai * HALF + m * 16; bf16_t* rowp = O + (size_t)row * ldc + col0; const float rs = rsv[ai][m];
; #pragma unroll
;                 for (int bj = 0; bj < 2; ++bj) { f32x4 v0 = acc[ai][bj][m][0] * rs, v1 = acc[ai][bj][m][1] * rs;
;                     if (ACT == 1) {
; #pragma unroll
;                         for (int j = 0; j < 4; ++j) { v0[j] = gelu_tanh(v0[j]); v1[j] = gelu_tanh(v1[j]); } }
;                     u32x4 w; w.x = cvt_pk_bf16(v0[0], v0[1]); w.y = cvt_pk_bf16(v0[2], v0[3]); w.z = cvt_pk_bf16(v1[0], v1[1]); w.w = cvt_pk_bf16(v1[2], v1[3]);
;                     *(u32x4*)(rowp + bj * HALF) = w; } }
	v_pk_mul_f32 v[96:97], v[96:97], v[156:157] op_sel:[0,1]
	v_pk_mul_f32 v[98:99], v[98:99], v[156:157] op_sel:[0,1]
	v_pk_mul_f32 v[144:145], v[100:101], s[98:99]
	v_pk_mul_f32 v[146:147], v[102:103], s[98:99]
	v_pk_mul_f32 v[148:149], v[96:97], s[98:99]
	v_pk_mul_f32 v[150:151], v[98:99], s[98:99]
	v_pk_mul_f32 v[144:145], v[100:101], v[144:145]
	v_pk_mul_f32 v[146:147], v[102:103], v[146:147]
	v_pk_mul_f32 v[148:149], v[96:97], v[148:149]
	v_pk_mul_f32 v[150:151], v[98:99], v[150:151]
	v_pk_fma_f32 v[144:145], v[100:101], v[144:145], v[100:101]
	v_pk_fma_f32 v[146:147], v[102:103], v[146:147], v[102:103]
	v_pk_fma_f32 v[148:149], v[96:97], v[148:149], v[96:97]
	v_pk_fma_f32 v[150:151], v[98:99], v[150:151], v[98:99]
	v_pk_mul_f32 v[144:145], v[144:145], s[100:101]
	v_pk_mul_f32 v[146:147], v[146:147], s[100:101]
	v_pk_mul_f32 v[148:149], v[148:149], s[100:101]
	v_pk_mul_f32 v[150:151], v[150:151], s[100:101]
	v_pk_mul_f32 v[144:145], v[144:145], v[166:167]
	v_pk_mul_f32 v[146:147], v[146:147], v[166:167]
	v_pk_mul_f32 v[148:149], v[148:149], v[166:167]
	v_pk_mul_f32 v[150:151], v[150:151], v[166:167]
	v_exp_f32_e32 v144, v144
	v_exp_f32_e32 v145, v145
	v_exp_f32_e32 v146, v146
	v_exp_f32_e32 v147, v147
	v_exp_f32_e32 v148, v148
	v_exp_f32_e32 v149, v149
	v_exp_f32_e32 v150, v150
	v_exp_f32_e32 v151, v151
	v_add_f32_e32 v144, 1.0, v144
	v_add_f32_e32 v145, 1.0, v145
	v_add_f32_e32 v146, 1.0, v146
	v_add_f32_e32 v147, 1.0, v147
	v_add_f32_e32 v148, 1.0, v148
	v_add_f32_e32 v149, 1.0, v149
	v_add_f32_e32 v150, 1.0, v150
	v_add_f32_e32 v151, 1.0, v151
	v_rcp_f32_e32 v144, v144
	v_rcp_f32_e32 v145, v145
	v_rcp_f32_e32 v146, v146
	v_rcp_f32_e32 v147, v147
	v_rcp_f32_e32 v148, v148
	v_rcp_f32_e32 v149, v149
	v_rcp_f32_e32 v150, v150
	v_rcp_f32_e32 v151, v151
	v_nop
	v_pk_mul_f32 v[100:101], v[100:101], v[144:145]
	v_pk_mul_f32 v[102:103], v[102:103], v[146:147]
	v_pk_mul_f32 v[96:97], v[96:97], v[148:149]
	v_pk_mul_f32 v[98:99], v[98:99], v[150:151]
	v_cvt_pk_bf16_f32 v100, v100, v101
	v_cvt_pk_bf16_f32 v101, v102, v103
	v_cvt_pk_bf16_f32 v102, v96, v97
	v_cvt_pk_bf16_f32 v103, v98, v99
	global_store_dwordx4 v[142:143], v[100:103], off offset:256
	v_lshl_add_u64 v[142:143], v[142:143], 0, s[10:11]
	v_pk_mul_f32 v[92:93], v[92:93], v[158:159] op_sel_hi:[1,0]
	v_pk_mul_f32 v[94:95], v[94:95], v[158:159] op_sel_hi:[1,0]
	v_pk_mul_f32 v[88:89], v[88:89], v[158:159] op_sel_hi:[1,0]
	v_pk_mul_f32 v[90:91], v[90:91], v[158:159] op_sel_hi:[1,0]
	v_pk_mul_f32 v[144:145], v[92:93], s[98:99]
	v_pk_mul_f32 v[146:147], v[94:95], s[98:99]
	v_pk_mul_f32 v[148:149], v[88:89], s[98:99]
	v_pk_mul_f32 v[150:151], v[90:91], s[98:99]
	v_pk_mul_f32 v[144:145], v[92:93], v[144:145]
	v_pk_mul_f32 v[146:147], v[94:95], v[146:147]
	v_pk_mul_f32 v[148:149], v[88:89], v[148:149]
	v_pk_mul_f32 v[150:151], v[90:91], v[150:151]
	v_pk_fma_f32 v[144:145], v[92:93], v[144:145], v[92:93]
	v_pk_fma_f32 v[146:147], v[94:95], v[146:147], v[94:95]
	v_pk_fma_f32 v[148:149], v[88:89], v[148:149], v[88:89]
	v_pk_fma_f32 v[150:151], v[90:91], v[150:151], v[90:91]
	v_pk_mul_f32 v[144:145], v[144:145], s[100:101]
	v_pk_mul_f32 v[146:147], v[146:147], s[100:101]
	v_pk_mul_f32 v[148:149], v[148:149], s[100:101]
	v_pk_mul_f32 v[150:151], v[150:151], s[100:101]
	v_pk_mul_f32 v[144:145], v[144:145], v[166:167]
	v_pk_mul_f32 v[146:147], v[146:147], v[166:167]
	v_pk_mul_f32 v[148:149], v[148:149], v[166:167]
	v_pk_mul_f32 v[150:151], v[150:151], v[166:167]
	v_exp_f32_e32 v144, v144
	v_exp_f32_e32 v145, v145
	v_exp_f32_e32 v146, v146
	v_exp_f32_e32 v147, v147
	v_exp_f32_e32 v148, v148
	v_exp_f32_e32 v149, v149
	v_exp_f32_e32 v150, v150
	v_exp_f32_e32 v151, v151
	v_add_f32_e32 v144, 1.0, v144
	v_add_f32_e32 v145, 1.0, v145
	v_add_f32_e32 v146, 1.0, v146
	v_add_f32_e32 v147, 1.0, v147
	v_add_f32_e32 v148, 1.0, v148
	v_add_f32_e32 v149, 1.0, v149
	v_add_f32_e32 v150, 1.0, v150
	v_add_f32_e32 v151, 1.0, v151
	v_rcp_f32_e32 v144, v144
	v_rcp_f32_e32 v145, v145
	v_rcp_f32_e32 v146, v146
	v_rcp_f32_e32 v147, v147
	v_rcp_f32_e32 v148, v148
	v_rcp_f32_e32 v149, v149
	v_rcp_f32_e32 v150, v150
	v_rcp_f32_e32 v151, v151
	v_nop
	v_pk_mul_f32 v[92:93], v[92:93], v[144:145]
	v_pk_mul_f32 v[94:95], v[94:95], v[146:147]
	v_pk_mul_f32 v[88:89], v[88:89], v[148:149]
	v_pk_mul_f32 v[90:91], v[90:91], v[150:151]
	v_cvt_pk_bf16_f32 v92, v92, v93
	v_cvt_pk_bf16_f32 v93, v94, v95
	v_cvt_pk_bf16_f32 v94, v88, v89
	v_cvt_pk_bf16_f32 v95, v90, v91
	global_store_dwordx4 v[142:143], v[92:95], off
	v_pk_mul_f32 v[84:85], v[84:85], v[158:159] op_sel_hi:[1,0]
	v_pk_mul_f32 v[86:87], v[86:87], v[158:159] op_sel_hi:[1,0]
	v_pk_mul_f32 v[80:81], v[80:81], v[158:159] op_sel_hi:[1,0]
	v_pk_mul_f32 v[82:83], v[82:83], v[158:159] op_sel_hi:[1,0]
	v_pk_mul_f32 v[144:145], v[84:85], s[98:99]
	v_pk_mul_f32 v[146:147], v[86:87], s[98:99]
	v_pk_mul_f32 v[148:149], v[80:81], s[98:99]
	v_pk_mul_f32 v[150:151], v[82:83], s[98:99]
	v_pk_mul_f32 v[144:145], v[84:85], v[144:145]
	v_pk_mul_f32 v[146:147], v[86:87], v[146:147]
	v_pk_mul_f32 v[148:149], v[80:81], v[148:149]
	v_pk_mul_f32 v[150:151], v[82:83], v[150:151]
	v_pk_fma_f32 v[144:145], v[84:85], v[144:145], v[84:85]
	v_pk_fma_f32 v[146:147], v[86:87], v[146:147], v[86:87]
	v_pk_fma_f32 v[148:149], v[80:81], v[148:149], v[80:81]
	v_pk_fma_f32 v[150:151], v[82:83], v[150:151], v[82:83]
	v_pk_mul_f32 v[144:145], v[144:145], s[100:101]
	v_pk_mul_f32 v[146:147], v[146:147], s[100:101]
	v_pk_mul_f32 v[148:149], v[148:149], s[100:101]
	v_pk_mul_f32 v[150:151], v[150:151], s[100:101]
	v_pk_mul_f32 v[144:145], v[144:145], v[166:167]
	v_pk_mul_f32 v[146:147], v[146:147], v[166:167]
; __device__ __forceinline__ unsigned cvt_pk_bf16(float lo, float hi) { unsigned r; asm volatile("v_cvt_pk_bf16_f32 %0, %1, %2" : "=v"(r) : "v"(lo), "v"(hi)); return r; }
; __device__ __forceinline__ float gelu_tanh(float x) { const float u = 0.7978845608028654f * (x + 0.044715f * x * x * x); return x * fast_rcp(1.0f + fast_exp2(-2.0f * LOG2E * u)); }
;     __device__ __forceinline__ void operator()(const f32x4 (&acc)[2][2][4][2], const Unit& u, int wr, int wc, int fr, int fq) const {
;     ...
;             for (int m = 0; m < 4; ++m) { const int row = row0 + ai * HALF + m * 16; bf16_t* rowp = O + (size_t)row * ldc + col0; const float rs = rsv[ai][m];
; #pragma unroll
;                 for (int bj = 0; bj < 2; ++bj) { f32x4 v0 = acc[ai][bj][m][0] * rs, v1 = acc[ai][bj][m][1] * rs;
;                     if (ACT == 1) {
; #pragma unroll
;                         for (int j = 0; j < 4; ++j) { v0[j] = gelu_tanh(v0[j]); v1[j] = gelu_tanh(v1[j]); } }
;                     u32x4 w; w.x = cvt_pk_bf16(v0[0], v0[1]); w.y = cvt_pk_bf16(v0[2], v0[3]); w.z = cvt_pk_bf16(v1[0], v1[1]); w.w = cvt_pk_bf16(v1[2], v1[3]);
;                     *(u32x4*)(rowp + bj * HALF) = w; } }
	v_pk_mul_f32 v[148:149], v[148:149], v[166:167]
	v_pk_mul_f32 v[150:151], v[150:151], v[166:167]
	v_exp_f32_e32 v144, v144
	v_exp_f32_e32 v145, v145
	v_exp_f32_e32 v146, v146
	v_exp_f32_e32 v147, v147
	v_exp_f32_e32 v148, v148
	v_exp_f32_e32 v149, v149
	v_exp_f32_e32 v150, v150
	v_exp_f32_e32 v151, v151
	v_add_f32_e32 v144, 1.0, v144
	v_add_f32_e32 v145, 1.0, v145
	v_add_f32_e32 v146, 1.0, v146
	v_add_f32_e32 v147, 1.0, v147
	v_add_f32_e32 v148, 1.0, v148
	v_add_f32_e32 v149, 1.0, v149
	v_add_f32_e32 v150, 1.0, v150
	v_add_f32_e32 v151, 1.0, v151
	v_rcp_f32_e32 v144, v144
	v_rcp_f32_e32 v145, v145
	v_rcp_f32_e32 v146, v146
	v_rcp_f32_e32 v147, v147
	v_rcp_f32_e32 v148, v148
	v_rcp_f32_e32 v149, v149
	v_rcp_f32_e32 v150, v150
	v_rcp_f32_e32 v151, v151
	v_nop
	v_pk_mul_f32 v[84:85], v[84:85], v[144:145]
	v_pk_mul_f32 v[86:87], v[86:87], v[146:147]
	v_pk_mul_f32 v[80:81], v[80:81], v[148:149]
	v_pk_mul_f32 v[82:83], v[82:83], v[150:151]
	v_cvt_pk_bf16_f32 v84, v84, v85
	v_cvt_pk_bf16_f32 v85, v86, v87
	v_cvt_pk_bf16_f32 v86, v80, v81
	v_cvt_pk_bf16_f32 v87, v82, v83
	global_store_dwordx4 v[142:143], v[84:87], off offset:256
	v_lshl_add_u64 v[142:143], v[142:143], 0, s[10:11]
	v_pk_mul_f32 v[76:77], v[76:77], v[158:159] op_sel:[0,1]
	v_pk_mul_f32 v[78:79], v[78:79], v[158:159] op_sel:[0,1]
	v_pk_mul_f32 v[72:73], v[72:73], v[158:159] op_sel:[0,1]
	v_pk_mul_f32 v[74:75], v[74:75], v[158:159] op_sel:[0,1]
	v_pk_mul_f32 v[144:145], v[76:77], s[98:99]
	v_pk_mul_f32 v[146:147], v[78:79], s[98:99]
	v_pk_mul_f32 v[148:149], v[72:73], s[98:99]
	v_pk_mul_f32 v[150:151], v[74:75], s[98:99]
	v_pk_mul_f32 v[144:145], v[76:77], v[144:145]
	v_pk_mul_f32 v[146:147], v[78:79], v[146:147]
	v_pk_mul_f32 v[148:149], v[72:73], v[148:149]
	v_pk_mul_f32 v[150:151], v[74:75], v[150:151]
	v_pk_fma_f32 v[144:145], v[76:77], v[144:145], v[76:77]
	v_pk_fma_f32 v[146:147], v[78:79], v[146:147], v[78:79]
	v_pk_fma_f32 v[148:149], v[72:73], v[148:149], v[72:73]
	v_pk_fma_f32 v[150:151], v[74:75], v[150:151], v[74:75]
	v_pk_mul_f32 v[144:145], v[144:145], s[100:101]
	v_pk_mul_f32 v[146:147], v[146:147], s[100:101]
	v_pk_mul_f32 v[148:149], v[148:149], s[100:101]
	v_pk_mul_f32 v[150:151], v[150:151], s[100:101]
	v_pk_mul_f32 v[144:145], v[144:145], v[166:167]
	v_pk_mul_f32 v[146:147], v[146:147], v[166:167]
	v_pk_mul_f32 v[148:149], v[148:149], v[166:167]
	v_pk_mul_f32 v[150:151], v[150:151], v[166:167]
	v_exp_f32_e32 v144, v144
	v_exp_f32_e32 v145, v145
	v_exp_f32_e32 v146, v146
	v_exp_f32_e32 v147, v147
	v_exp_f32_e32 v148, v148
	v_exp_f32_e32 v149, v149
	v_exp_f32_e32 v150, v150
	v_exp_f32_e32 v151, v151
	v_add_f32_e32 v144, 1.0, v144
	v_add_f32_e32 v145, 1.0, v145
	v_add_f32_e32 v146, 1.0, v146
	v_add_f32_e32 v147, 1.0, v147
	v_add_f32_e32 v148, 1.0, v148
	v_add_f32_e32 v149, 1.0, v149
	v_add_f32_e32 v150, 1.0, v150
	v_add_f32_e32 v151, 1.0, v151
	v_rcp_f32_e32 v144, v144
	v_rcp_f32_e32 v145, v145
	v_rcp_f32_e32 v146, v146
	v_rcp_f32_e32 v147, v147
	v_rcp_f32_e32 v148, v148
	v_rcp_f32_e32 v149, v149
	v_rcp_f32_e32 v150, v150
	v_rcp_f32_e32 v151, v151
	v_nop
	v_pk_mul_f32 v[76:77], v[76:77], v[144:145]
	v_pk_mul_f32 v[78:79], v[78:79], v[146:147]
	v_pk_mul_f32 v[72:73], v[72:73], v[148:149]
	v_pk_mul_f32 v[74:75], v[74:75], v[150:151]
	v_cvt_pk_bf16_f32 v76, v76, v77
	v_cvt_pk_bf16_f32 v77, v78, v79
	v_cvt_pk_bf16_f32 v78, v72, v73
	v_cvt_pk_bf16_f32 v79, v74, v75
	global_store_dwordx4 v[142:143], v[76:79], off
	v_pk_mul_f32 v[68:69], v[68:69], v[158:159] op_sel:[0,1]
	v_pk_mul_f32 v[70:71], v[70:71], v[158:159] op_sel:[0,1]
	v_pk_mul_f32 v[64:65], v[64:65], v[158:159] op_sel:[0,1]
	v_pk_mul_f32 v[66:67], v[66:67], v[158:159] op_sel:[0,1]
	v_pk_mul_f32 v[144:145], v[68:69], s[98:99]
	v_pk_mul_f32 v[146:147], v[70:71], s[98:99]
	v_pk_mul_f32 v[148:149], v[64:65], s[98:99]
	v_pk_mul_f32 v[150:151], v[66:67], s[98:99]
	v_pk_mul_f32 v[144:145], v[68:69], v[144:145]
	v_pk_mul_f32 v[146:147], v[70:71], v[146:147]
	v_pk_mul_f32 v[148:149], v[64:65], v[148:149]
	v_pk_mul_f32 v[150:151], v[66:67], v[150:151]
	v_pk_fma_f32 v[144:145], v[68:69], v[144:145], v[68:69]
	v_pk_fma_f32 v[146:147], v[70:71], v[146:147], v[70:71]
	v_pk_fma_f32 v[148:149], v[64:65], v[148:149], v[64:65]
	v_pk_fma_f32 v[150:151], v[66:67], v[150:151], v[66:67]
	v_pk_mul_f32 v[144:145], v[144:145], s[100:101]
	v_pk_mul_f32 v[146:147], v[146:147], s[100:101]
	v_pk_mul_f32 v[148:149], v[148:149], s[100:101]
	v_pk_mul_f32 v[150:151], v[150:151], s[100:101]
	v_pk_mul_f32 v[144:145], v[144:145], v[166:167]
	v_pk_mul_f32 v[146:147], v[146:147], v[166:167]
	v_pk_mul_f32 v[148:149], v[148:149], v[166:167]
	v_pk_mul_f32 v[150:151], v[150:151], v[166:167]
	v_exp_f32_e32 v144, v144
	v_exp_f32_e32 v145, v145
	v_exp_f32_e32 v146, v146
	v_exp_f32_e32 v147, v147
	v_exp_f32_e32 v148, v148
	v_exp_f32_e32 v149, v149
	v_exp_f32_e32 v150, v150
	v_exp_f32_e32 v151, v151
	v_add_f32_e32 v144, 1.0, v144
	v_add_f32_e32 v145, 1.0, v145
	v_add_f32_e32 v146, 1.0, v146
	v_add_f32_e32 v147, 1.0, v147
	v_add_f32_e32 v148, 1.0, v148
	v_add_f32_e32 v149, 1.0, v149
	v_add_f32_e32 v150, 1.0, v150
	v_add_f32_e32 v151, 1.0, v151
	v_rcp_f32_e32 v144, v144
	v_rcp_f32_e32 v145, v145
	v_rcp_f32_e32 v146, v146
	v_rcp_f32_e32 v147, v147
	v_rcp_f32_e32 v148, v148
	v_rcp_f32_e32 v149, v149
	v_rcp_f32_e32 v150, v150
	v_rcp_f32_e32 v151, v151
	v_nop
	v_pk_mul_f32 v[68:69], v[68:69], v[144:145]
	v_pk_mul_f32 v[70:71], v[70:71], v[146:147]
	v_pk_mul_f32 v[64:65], v[64:65], v[148:149]
	v_pk_mul_f32 v[66:67], v[66:67], v[150:151]
	v_cvt_pk_bf16_f32 v68, v68, v69
	v_cvt_pk_bf16_f32 v69, v70, v71
	v_cvt_pk_bf16_f32 v70, v64, v65
	v_cvt_pk_bf16_f32 v71, v66, v67
; __device__ __forceinline__ unsigned cvt_pk_bf16(float lo, float hi) { unsigned r; asm volatile("v_cvt_pk_bf16_f32 %0, %1, %2" : "=v"(r) : "v"(lo), "v"(hi)); return r; }
; __device__ __forceinline__ float gelu_tanh(float x) { const float u = 0.7978845608028654f * (x + 0.044715f * x * x * x); return x * fast_rcp(1.0f + fast_exp2(-2.0f * LOG2E * u)); }
;     __device__ __forceinline__ void operator()(const f32x4 (&acc)[2][2][4][2], const Unit& u, int wr, int wc, int fr, int fq) const {
;     ...
;             for (int m = 0; m < 4; ++m) { const int row = row0 + ai * HALF + m * 16; bf16_t* rowp = O + (size_t)row * ldc + col0; const float rs = rsv[ai][m];
; #pragma unroll
;                 for (int bj = 0; bj < 2; ++bj) { f32x4 v0 = acc[ai][bj][m][0] * rs, v1 = acc[ai][bj][m][1] * rs;
;                     if (ACT == 1) {
; #pragma unroll
;                         for (int j = 0; j < 4; ++j) { v0[j] = gelu_tanh(v0[j]); v1[j] = gelu_tanh(v1[j]); } }
;                     u32x4 w; w.x = cvt_pk_bf16(v0[0], v0[1]); w.y = cvt_pk_bf16(v0[2], v0[3]); w.z = cvt_pk_bf16(v1[0], v1[1]); w.w = cvt_pk_bf16(v1[2], v1[3]);
;                     *(u32x4*)(rowp + bj * HALF) = w; } }
	global_store_dwordx4 v[142:143], v[68:71], off offset:256
	v_lshl_add_u64 v[142:143], v[142:143], 0, s[10:11]
	v_lshl_add_u64 v[142:143], v[142:143], 0, s[10:11]
	v_lshl_add_u64 v[142:143], v[142:143], 0, s[10:11]
	v_lshl_add_u64 v[142:143], v[142:143], 0, s[10:11]
	v_lshl_add_u64 v[142:143], v[142:143], 0, s[10:11]
	v_pk_mul_f32 v[60:61], v[60:61], v[162:163] op_sel_hi:[1,0]
	v_pk_mul_f32 v[62:63], v[62:63], v[162:163] op_sel_hi:[1,0]
	v_pk_mul_f32 v[56:57], v[56:57], v[162:163] op_sel_hi:[1,0]
	v_pk_mul_f32 v[58:59], v[58:59], v[162:163] op_sel_hi:[1,0]
	v_pk_mul_f32 v[144:145], v[60:61], s[98:99]
	v_pk_mul_f32 v[146:147], v[62:63], s[98:99]
	v_pk_mul_f32 v[148:149], v[56:57], s[98:99]
	v_pk_mul_f32 v[150:151], v[58:59], s[98:99]
	v_pk_mul_f32 v[144:145], v[60:61], v[144:145]
	v_pk_mul_f32 v[146:147], v[62:63], v[146:147]
	v_pk_mul_f32 v[148:149], v[56:57], v[148:149]
	v_pk_mul_f32 v[150:151], v[58:59], v[150:151]
	v_pk_fma_f32 v[144:145], v[60:61], v[144:145], v[60:61]
	v_pk_fma_f32 v[146:147], v[62:63], v[146:147], v[62:63]
	v_pk_fma_f32 v[148:149], v[56:57], v[148:149], v[56:57]
	v_pk_fma_f32 v[150:151], v[58:59], v[150:151], v[58:59]
	v_pk_mul_f32 v[144:145], v[144:145], s[100:101]
	v_pk_mul_f32 v[146:147], v[146:147], s[100:101]
	v_pk_mul_f32 v[148:149], v[148:149], s[100:101]
	v_pk_mul_f32 v[150:151], v[150:151], s[100:101]
	v_pk_mul_f32 v[144:145], v[144:145], v[166:167]
	v_pk_mul_f32 v[146:147], v[146:147], v[166:167]
	v_pk_mul_f32 v[148:149], v[148:149], v[166:167]
	v_pk_mul_f32 v[150:151], v[150:151], v[166:167]
	v_exp_f32_e32 v144, v144
	v_exp_f32_e32 v145, v145
	v_exp_f32_e32 v146, v146
	v_exp_f32_e32 v147, v147
	v_exp_f32_e32 v148, v148
	v_exp_f32_e32 v149, v149
	v_exp_f32_e32 v150, v150
	v_exp_f32_e32 v151, v151
	v_add_f32_e32 v144, 1.0, v144
	v_add_f32_e32 v145, 1.0, v145
	v_add_f32_e32 v146, 1.0, v146
	v_add_f32_e32 v147, 1.0, v147
	v_add_f32_e32 v148, 1.0, v148
	v_add_f32_e32 v149, 1.0, v149
	v_add_f32_e32 v150, 1.0, v150
	v_add_f32_e32 v151, 1.0, v151
	v_rcp_f32_e32 v144, v144
	v_rcp_f32_e32 v145, v145
	v_rcp_f32_e32 v146, v146
	v_rcp_f32_e32 v147, v147
	v_rcp_f32_e32 v148, v148
	v_rcp_f32_e32 v149, v149
	v_rcp_f32_e32 v150, v150
	v_rcp_f32_e32 v151, v151
	v_nop
	v_pk_mul_f32 v[60:61], v[60:61], v[144:145]
	v_pk_mul_f32 v[62:63], v[62:63], v[146:147]
	v_pk_mul_f32 v[56:57], v[56:57], v[148:149]
	v_pk_mul_f32 v[58:59], v[58:59], v[150:151]
	v_cvt_pk_bf16_f32 v60, v60, v61
	v_cvt_pk_bf16_f32 v61, v62, v63
	v_cvt_pk_bf16_f32 v62, v56, v57
	v_cvt_pk_bf16_f32 v63, v58, v59
	global_store_dwordx4 v[142:143], v[60:63], off
	v_pk_mul_f32 v[52:53], v[52:53], v[162:163] op_sel_hi:[1,0]
	v_pk_mul_f32 v[54:55], v[54:55], v[162:163] op_sel_hi:[1,0]
	v_pk_mul_f32 v[48:49], v[48:49], v[162:163] op_sel_hi:[1,0]
	v_pk_mul_f32 v[50:51], v[50:51], v[162:163] op_sel_hi:[1,0]
	v_pk_mul_f32 v[144:145], v[52:53], s[98:99]
	v_pk_mul_f32 v[146:147], v[54:55], s[98:99]
	v_pk_mul_f32 v[148:149], v[48:49], s[98:99]
	v_pk_mul_f32 v[150:151], v[50:51], s[98:99]
	v_pk_mul_f32 v[144:145], v[52:53], v[144:145]
	v_pk_mul_f32 v[146:147], v[54:55], v[146:147]
	v_pk_mul_f32 v[148:149], v[48:49], v[148:149]
	v_pk_mul_f32 v[150:151], v[50:51], v[150:151]
	v_pk_fma_f32 v[144:145], v[52:53], v[144:145], v[52:53]
	v_pk_fma_f32 v[146:147], v[54:55], v[146:147], v[54:55]
	v_pk_fma_f32 v[148:149], v[48:49], v[148:149], v[48:49]
	v_pk_fma_f32 v[150:151], v[50:51], v[150:151], v[50:51]
	v_pk_mul_f32 v[144:145], v[144:145], s[100:101]
	v_pk_mul_f32 v[146:147], v[146:147], s[100:101]
	v_pk_mul_f32 v[148:149], v[148:149], s[100:101]
	v_pk_mul_f32 v[150:151], v[150:151], s[100:101]
	v_pk_mul_f32 v[144:145], v[144:145], v[166:167]
	v_pk_mul_f32 v[146:147], v[146:147], v[166:167]
	v_pk_mul_f32 v[148:149], v[148:149], v[166:167]
	v_pk_mul_f32 v[150:151], v[150:151], v[166:167]
	v_exp_f32_e32 v144, v144
	v_exp_f32_e32 v145, v145
	v_exp_f32_e32 v146, v146
	v_exp_f32_e32 v147, v147
	v_exp_f32_e32 v148, v148
	v_exp_f32_e32 v149, v149
	v_exp_f32_e32 v150, v150
	v_exp_f32_e32 v151, v151
	v_add_f32_e32 v144, 1.0, v144
	v_add_f32_e32 v145, 1.0, v145
	v_add_f32_e32 v146, 1.0, v146
	v_add_f32_e32 v147, 1.0, v147
	v_add_f32_e32 v148, 1.0, v148
	v_add_f32_e32 v149, 1.0, v149
	v_add_f32_e32 v150, 1.0, v150
	v_add_f32_e32 v151, 1.0, v151
	v_rcp_f32_e32 v144, v144
	v_rcp_f32_e32 v145, v145
	v_rcp_f32_e32 v146, v146
	v_rcp_f32_e32 v147, v147
	v_rcp_f32_e32 v148, v148
	v_rcp_f32_e32 v149, v149
	v_rcp_f32_e32 v150, v150
	v_rcp_f32_e32 v151, v151
	v_nop
	v_pk_mul_f32 v[52:53], v[52:53], v[144:145]
	v_pk_mul_f32 v[54:55], v[54:55], v[146:147]
	v_pk_mul_f32 v[48:49], v[48:49], v[148:149]
	v_pk_mul_f32 v[50:51], v[50:51], v[150:151]
	v_cvt_pk_bf16_f32 v52, v52, v53
	v_cvt_pk_bf16_f32 v53, v54, v55
	v_cvt_pk_bf16_f32 v54, v48, v49
	v_cvt_pk_bf16_f32 v55, v50, v51
	global_store_dwordx4 v[142:143], v[52:55], off offset:256
	v_lshl_add_u64 v[142:143], v[142:143], 0, s[10:11]
	v_pk_mul_f32 v[44:45], v[44:45], v[162:163] op_sel:[0,1]
	v_pk_mul_f32 v[46:47], v[46:47], v[162:163] op_sel:[0,1]
	v_pk_mul_f32 v[40:41], v[40:41], v[162:163] op_sel:[0,1]
	v_pk_mul_f32 v[42:43], v[42:43], v[162:163] op_sel:[0,1]
	v_pk_mul_f32 v[144:145], v[44:45], s[98:99]
	v_pk_mul_f32 v[146:147], v[46:47], s[98:99]
	v_pk_mul_f32 v[148:149], v[40:41], s[98:99]
	v_pk_mul_f32 v[150:151], v[42:43], s[98:99]
	v_pk_mul_f32 v[144:145], v[44:45], v[144:145]
	v_pk_mul_f32 v[146:147], v[46:47], v[146:147]
	v_pk_mul_f32 v[148:149], v[40:41], v[148:149]
	v_pk_mul_f32 v[150:151], v[42:43], v[150:151]
	v_pk_fma_f32 v[144:145], v[44:45], v[144:145], v[44:45]
	v_pk_fma_f32 v[146:147], v[46:47], v[146:147], v[46:47]
; __device__ __forceinline__ unsigned cvt_pk_bf16(float lo, float hi) { unsigned r; asm volatile("v_cvt_pk_bf16_f32 %0, %1, %2" : "=v"(r) : "v"(lo), "v"(hi)); return r; }
; __device__ __forceinline__ float gelu_tanh(float x) { const float u = 0.7978845608028654f * (x + 0.044715f * x * x * x); return x * fast_rcp(1.0f + fast_exp2(-2.0f * LOG2E * u)); }
;     __device__ __forceinline__ void operator()(const f32x4 (&acc)[2][2][4][2], const Unit& u, int wr, int wc, int fr, int fq) const {
;     ...
;             for (int m = 0; m < 4; ++m) { const int row = row0 + ai * HALF + m * 16; bf16_t* rowp = O + (size_t)row * ldc + col0; const float rs = rsv[ai][m];
; #pragma unroll
;                 for (int bj = 0; bj < 2; ++bj) { f32x4 v0 = acc[ai][bj][m][0] * rs, v1 = acc[ai][bj][m][1] * rs;
;                     if (ACT == 1) {
; #pragma unroll
;                         for (int j = 0; j < 4; ++j) { v0[j] = gelu_tanh(v0[j]); v1[j] = gelu_tanh(v1[j]); } }
;                     u32x4 w; w.x = cvt_pk_bf16(v0[0], v0[1]); w.y = cvt_pk_bf16(v0[2], v0[3]); w.z = cvt_pk_bf16(v1[0], v1[1]); w.w = cvt_pk_bf16(v1[2], v1[3]);
;                     *(u32x4*)(rowp + bj * HALF) = w; } }
	v_pk_fma_f32 v[148:149], v[40:41], v[148:149], v[40:41]
	v_pk_fma_f32 v[150:151], v[42:43], v[150:151], v[42:43]
	v_pk_mul_f32 v[144:145], v[144:145], s[100:101]
	v_pk_mul_f32 v[146:147], v[146:147], s[100:101]
	v_pk_mul_f32 v[148:149], v[148:149], s[100:101]
	v_pk_mul_f32 v[150:151], v[150:151], s[100:101]
	v_pk_mul_f32 v[144:145], v[144:145], v[166:167]
	v_pk_mul_f32 v[146:147], v[146:147], v[166:167]
	v_pk_mul_f32 v[148:149], v[148:149], v[166:167]
	v_pk_mul_f32 v[150:151], v[150:151], v[166:167]
	v_exp_f32_e32 v144, v144
	v_exp_f32_e32 v145, v145
	v_exp_f32_e32 v146, v146
	v_exp_f32_e32 v147, v147
	v_exp_f32_e32 v148, v148
	v_exp_f32_e32 v149, v149
	v_exp_f32_e32 v150, v150
	v_exp_f32_e32 v151, v151
	v_add_f32_e32 v144, 1.0, v144
	v_add_f32_e32 v145, 1.0, v145
	v_add_f32_e32 v146, 1.0, v146
	v_add_f32_e32 v147, 1.0, v147
	v_add_f32_e32 v148, 1.0, v148
	v_add_f32_e32 v149, 1.0, v149
	v_add_f32_e32 v150, 1.0, v150
	v_add_f32_e32 v151, 1.0, v151
	v_rcp_f32_e32 v144, v144
	v_rcp_f32_e32 v145, v145
	v_rcp_f32_e32 v146, v146
	v_rcp_f32_e32 v147, v147
	v_rcp_f32_e32 v148, v148
	v_rcp_f32_e32 v149, v149
	v_rcp_f32_e32 v150, v150
	v_rcp_f32_e32 v151, v151
	v_nop
	v_pk_mul_f32 v[44:45], v[44:45], v[144:145]
	v_pk_mul_f32 v[46:47], v[46:47], v[146:147]
	v_pk_mul_f32 v[40:41], v[40:41], v[148:149]
	v_pk_mul_f32 v[42:43], v[42:43], v[150:151]
	v_cvt_pk_bf16_f32 v44, v44, v45
	v_cvt_pk_bf16_f32 v45, v46, v47
	v_cvt_pk_bf16_f32 v46, v40, v41
	v_cvt_pk_bf16_f32 v47, v42, v43
	global_store_dwordx4 v[142:143], v[44:47], off
	v_pk_mul_f32 v[36:37], v[36:37], v[162:163] op_sel:[0,1]
	v_pk_mul_f32 v[38:39], v[38:39], v[162:163] op_sel:[0,1]
	v_pk_mul_f32 v[32:33], v[32:33], v[162:163] op_sel:[0,1]
	v_pk_mul_f32 v[34:35], v[34:35], v[162:163] op_sel:[0,1]
	v_pk_mul_f32 v[144:145], v[36:37], s[98:99]
	v_pk_mul_f32 v[146:147], v[38:39], s[98:99]
	v_pk_mul_f32 v[148:149], v[32:33], s[98:99]
	v_pk_mul_f32 v[150:151], v[34:35], s[98:99]
	v_pk_mul_f32 v[144:145], v[36:37], v[144:145]
	v_pk_mul_f32 v[146:147], v[38:39], v[146:147]
	v_pk_mul_f32 v[148:149], v[32:33], v[148:149]
	v_pk_mul_f32 v[150:151], v[34:35], v[150:151]
	v_pk_fma_f32 v[144:145], v[36:37], v[144:145], v[36:37]
	v_pk_fma_f32 v[146:147], v[38:39], v[146:147], v[38:39]
	v_pk_fma_f32 v[148:149], v[32:33], v[148:149], v[32:33]
	v_pk_fma_f32 v[150:151], v[34:35], v[150:151], v[34:35]
	v_pk_mul_f32 v[144:145], v[144:145], s[100:101]
	v_pk_mul_f32 v[146:147], v[146:147], s[100:101]
	v_pk_mul_f32 v[148:149], v[148:149], s[100:101]
	v_pk_mul_f32 v[150:151], v[150:151], s[100:101]
	v_pk_mul_f32 v[144:145], v[144:145], v[166:167]
	v_pk_mul_f32 v[146:147], v[146:147], v[166:167]
	v_pk_mul_f32 v[148:149], v[148:149], v[166:167]
	v_pk_mul_f32 v[150:151], v[150:151], v[166:167]
	v_exp_f32_e32 v144, v144
	v_exp_f32_e32 v145, v145
	v_exp_f32_e32 v146, v146
	v_exp_f32_e32 v147, v147
	v_exp_f32_e32 v148, v148
	v_exp_f32_e32 v149, v149
	v_exp_f32_e32 v150, v150
	v_exp_f32_e32 v151, v151
	v_add_f32_e32 v144, 1.0, v144
	v_add_f32_e32 v145, 1.0, v145
	v_add_f32_e32 v146, 1.0, v146
	v_add_f32_e32 v147, 1.0, v147
	v_add_f32_e32 v148, 1.0, v148
	v_add_f32_e32 v149, 1.0, v149
	v_add_f32_e32 v150, 1.0, v150
	v_add_f32_e32 v151, 1.0, v151
	v_rcp_f32_e32 v144, v144
	v_rcp_f32_e32 v145, v145
	v_rcp_f32_e32 v146, v146
	v_rcp_f32_e32 v147, v147
	v_rcp_f32_e32 v148, v148
	v_rcp_f32_e32 v149, v149
	v_rcp_f32_e32 v150, v150
	v_rcp_f32_e32 v151, v151
	v_nop
	v_pk_mul_f32 v[36:37], v[36:37], v[144:145]
	v_pk_mul_f32 v[38:39], v[38:39], v[146:147]
	v_pk_mul_f32 v[32:33], v[32:33], v[148:149]
	v_pk_mul_f32 v[34:35], v[34:35], v[150:151]
	v_cvt_pk_bf16_f32 v36, v36, v37
	v_cvt_pk_bf16_f32 v37, v38, v39
	v_cvt_pk_bf16_f32 v38, v32, v33
	v_cvt_pk_bf16_f32 v39, v34, v35
	global_store_dwordx4 v[142:143], v[36:39], off offset:256
	v_lshl_add_u64 v[142:143], v[142:143], 0, s[10:11]
	v_pk_mul_f32 v[28:29], v[28:29], v[164:165] op_sel_hi:[1,0]
	v_pk_mul_f32 v[30:31], v[30:31], v[164:165] op_sel_hi:[1,0]
	v_pk_mul_f32 v[24:25], v[24:25], v[164:165] op_sel_hi:[1,0]
	v_pk_mul_f32 v[26:27], v[26:27], v[164:165] op_sel_hi:[1,0]
	v_pk_mul_f32 v[144:145], v[28:29], s[98:99]
	v_pk_mul_f32 v[146:147], v[30:31], s[98:99]
	v_pk_mul_f32 v[148:149], v[24:25], s[98:99]
	v_pk_mul_f32 v[150:151], v[26:27], s[98:99]
	v_pk_mul_f32 v[144:145], v[28:29], v[144:145]
	v_pk_mul_f32 v[146:147], v[30:31], v[146:147]
	v_pk_mul_f32 v[148:149], v[24:25], v[148:149]
	v_pk_mul_f32 v[150:151], v[26:27], v[150:151]
	v_pk_fma_f32 v[144:145], v[28:29], v[144:145], v[28:29]
	v_pk_fma_f32 v[146:147], v[30:31], v[146:147], v[30:31]
	v_pk_fma_f32 v[148:149], v[24:25], v[148:149], v[24:25]
	v_pk_fma_f32 v[150:151], v[26:27], v[150:151], v[26:27]
	v_pk_mul_f32 v[144:145], v[144:145], s[100:101]
	v_pk_mul_f32 v[146:147], v[146:147], s[100:101]
	v_pk_mul_f32 v[148:149], v[148:149], s[100:101]
	v_pk_mul_f32 v[150:151], v[150:151], s[100:101]
	v_pk_mul_f32 v[144:145], v[144:145], v[166:167]
	v_pk_mul_f32 v[146:147], v[146:147], v[166:167]
	v_pk_mul_f32 v[148:149], v[148:149], v[166:167]
	v_pk_mul_f32 v[150:151], v[150:151], v[166:167]
	v_exp_f32_e32 v144, v144
	v_exp_f32_e32 v145, v145
	v_exp_f32_e32 v146, v146
	v_exp_f32_e32 v147, v147
	v_exp_f32_e32 v148, v148
	v_exp_f32_e32 v149, v149
	v_exp_f32_e32 v150, v150
	v_exp_f32_e32 v151, v151
	v_add_f32_e32 v144, 1.0, v144
	v_add_f32_e32 v145, 1.0, v145
	v_add_f32_e32 v146, 1.0, v146
	v_add_f32_e32 v147, 1.0, v147
	v_add_f32_e32 v148, 1.0, v148
	v_add_f32_e32 v149, 1.0, v149
	v_add_f32_e32 v150, 1.0, v150
	v_add_f32_e32 v151, 1.0, v151
	v_rcp_f32_e32 v144, v144
	v_rcp_f32_e32 v145, v145
	v_rcp_f32_e32 v146, v146
	v_rcp_f32_e32 v147, v147
; __device__ __forceinline__ unsigned cvt_pk_bf16(float lo, float hi) { unsigned r; asm volatile("v_cvt_pk_bf16_f32 %0, %1, %2" : "=v"(r) : "v"(lo), "v"(hi)); return r; }
; __device__ __forceinline__ float gelu_tanh(float x) { const float u = 0.7978845608028654f * (x + 0.044715f * x * x * x); return x * fast_rcp(1.0f + fast_exp2(-2.0f * LOG2E * u)); }
;     __device__ __forceinline__ void operator()(const f32x4 (&acc)[2][2][4][2], const Unit& u, int wr, int wc, int fr, int fq) const {
;     ...
;             for (int m = 0; m < 4; ++m) { const int row = row0 + ai * HALF + m * 16; bf16_t* rowp = O + (size_t)row * ldc + col0; const float rs = rsv[ai][m];
; #pragma unroll
;                 for (int bj = 0; bj < 2; ++bj) { f32x4 v0 = acc[ai][bj][m][0] * rs, v1 = acc[ai][bj][m][1] * rs;
;                     if (ACT == 1) {
; #pragma unroll
;                         for (int j = 0; j < 4; ++j) { v0[j] = gelu_tanh(v0[j]); v1[j] = gelu_tanh(v1[j]); } }
;                     u32x4 w; w.x = cvt_pk_bf16(v0[0], v0[1]); w.y = cvt_pk_bf16(v0[2], v0[3]); w.z = cvt_pk_bf16(v1[0], v1[1]); w.w = cvt_pk_bf16(v1[2], v1[3]);
;                     *(u32x4*)(rowp + bj * HALF) = w; } }
	v_rcp_f32_e32 v148, v148
	v_rcp_f32_e32 v149, v149
	v_rcp_f32_e32 v150, v150
	v_rcp_f32_e32 v151, v151
	v_nop
	v_pk_mul_f32 v[28:29], v[28:29], v[144:145]
	v_pk_mul_f32 v[30:31], v[30:31], v[146:147]
	v_pk_mul_f32 v[24:25], v[24:25], v[148:149]
	v_pk_mul_f32 v[26:27], v[26:27], v[150:151]
	v_cvt_pk_bf16_f32 v28, v28, v29
	v_cvt_pk_bf16_f32 v29, v30, v31
	v_cvt_pk_bf16_f32 v30, v24, v25
	v_cvt_pk_bf16_f32 v31, v26, v27
	global_store_dwordx4 v[142:143], v[28:31], off
	v_pk_mul_f32 v[20:21], v[20:21], v[164:165] op_sel_hi:[1,0]
	v_pk_mul_f32 v[22:23], v[22:23], v[164:165] op_sel_hi:[1,0]
	v_pk_mul_f32 v[16:17], v[16:17], v[164:165] op_sel_hi:[1,0]
	v_pk_mul_f32 v[18:19], v[18:19], v[164:165] op_sel_hi:[1,0]
	v_pk_mul_f32 v[144:145], v[20:21], s[98:99]
	v_pk_mul_f32 v[146:147], v[22:23], s[98:99]
	v_pk_mul_f32 v[148:149], v[16:17], s[98:99]
	v_pk_mul_f32 v[150:151], v[18:19], s[98:99]
	v_pk_mul_f32 v[144:145], v[20:21], v[144:145]
	v_pk_mul_f32 v[146:147], v[22:23], v[146:147]
	v_pk_mul_f32 v[148:149], v[16:17], v[148:149]
	v_pk_mul_f32 v[150:151], v[18:19], v[150:151]
	v_pk_fma_f32 v[144:145], v[20:21], v[144:145], v[20:21]
	v_pk_fma_f32 v[146:147], v[22:23], v[146:147], v[22:23]
	v_pk_fma_f32 v[148:149], v[16:17], v[148:149], v[16:17]
	v_pk_fma_f32 v[150:151], v[18:19], v[150:151], v[18:19]
	v_pk_mul_f32 v[144:145], v[144:145], s[100:101]
	v_pk_mul_f32 v[146:147], v[146:147], s[100:101]
	v_pk_mul_f32 v[148:149], v[148:149], s[100:101]
	v_pk_mul_f32 v[150:151], v[150:151], s[100:101]
	v_pk_mul_f32 v[144:145], v[144:145], v[166:167]
	v_pk_mul_f32 v[146:147], v[146:147], v[166:167]
	v_pk_mul_f32 v[148:149], v[148:149], v[166:167]
	v_pk_mul_f32 v[150:151], v[150:151], v[166:167]
	v_exp_f32_e32 v144, v144
	v_exp_f32_e32 v145, v145
	v_exp_f32_e32 v146, v146
	v_exp_f32_e32 v147, v147
	v_exp_f32_e32 v148, v148
	v_exp_f32_e32 v149, v149
	v_exp_f32_e32 v150, v150
	v_exp_f32_e32 v151, v151
	v_add_f32_e32 v144, 1.0, v144
	v_add_f32_e32 v145, 1.0, v145
	v_add_f32_e32 v146, 1.0, v146
	v_add_f32_e32 v147, 1.0, v147
	v_add_f32_e32 v148, 1.0, v148
	v_add_f32_e32 v149, 1.0, v149
	v_add_f32_e32 v150, 1.0, v150
	v_add_f32_e32 v151, 1.0, v151
	v_rcp_f32_e32 v144, v144
	v_rcp_f32_e32 v145, v145
	v_rcp_f32_e32 v146, v146
	v_rcp_f32_e32 v147, v147
	v_rcp_f32_e32 v148, v148
	v_rcp_f32_e32 v149, v149
	v_rcp_f32_e32 v150, v150
	v_rcp_f32_e32 v151, v151
	v_nop
	v_pk_mul_f32 v[20:21], v[20:21], v[144:145]
	v_pk_mul_f32 v[22:23], v[22:23], v[146:147]
	v_pk_mul_f32 v[16:17], v[16:17], v[148:149]
	v_pk_mul_f32 v[18:19], v[18:19], v[150:151]
	v_cvt_pk_bf16_f32 v20, v20, v21
	v_cvt_pk_bf16_f32 v21, v22, v23
	v_cvt_pk_bf16_f32 v22, v16, v17
	v_cvt_pk_bf16_f32 v23, v18, v19
	global_store_dwordx4 v[142:143], v[20:23], off offset:256
	v_lshl_add_u64 v[142:143], v[142:143], 0, s[10:11]
	v_pk_mul_f32 v[12:13], v[12:13], v[164:165] op_sel:[0,1]
	v_pk_mul_f32 v[14:15], v[14:15], v[164:165] op_sel:[0,1]
	v_pk_mul_f32 v[8:9], v[8:9], v[164:165] op_sel:[0,1]
	v_pk_mul_f32 v[10:11], v[10:11], v[164:165] op_sel:[0,1]
	v_pk_mul_f32 v[144:145], v[12:13], s[98:99]
	v_pk_mul_f32 v[146:147], v[14:15], s[98:99]
	v_pk_mul_f32 v[148:149], v[8:9], s[98:99]
	v_pk_mul_f32 v[150:151], v[10:11], s[98:99]
	v_pk_mul_f32 v[144:145], v[12:13], v[144:145]
	v_pk_mul_f32 v[146:147], v[14:15], v[146:147]
	v_pk_mul_f32 v[148:149], v[8:9], v[148:149]
	v_pk_mul_f32 v[150:151], v[10:11], v[150:151]
	v_pk_fma_f32 v[144:145], v[12:13], v[144:145], v[12:13]
	v_pk_fma_f32 v[146:147], v[14:15], v[146:147], v[14:15]
	v_pk_fma_f32 v[148:149], v[8:9], v[148:149], v[8:9]
	v_pk_fma_f32 v[150:151], v[10:11], v[150:151], v[10:11]
	v_pk_mul_f32 v[144:145], v[144:145], s[100:101]
	v_pk_mul_f32 v[146:147], v[146:147], s[100:101]
; __device__ __forceinline__ unsigned cvt_pk_bf16(float lo, float hi) { unsigned r; asm volatile("v_cvt_pk_bf16_f32 %0, %1, %2" : "=v"(r) : "v"(lo), "v"(hi)); return r; }
; __device__ __forceinline__ float gelu_tanh(float x) { const float u = 0.7978845608028654f * (x + 0.044715f * x * x * x); return x * fast_rcp(1.0f + fast_exp2(-2.0f * LOG2E * u)); }
;     __device__ __forceinline__ void operator()(const f32x4 (&acc)[2][2][4][2], const Unit& u, int wr, int wc, int fr, int fq) const {
;     ...
;             for (int m = 0; m < 4; ++m) { const int row = row0 + ai * HALF + m * 16; bf16_t* rowp = O + (size_t)row * ldc + col0; const float rs = rsv[ai][m];
; #pragma unroll
;                 for (int bj = 0; bj < 2; ++bj) { f32x4 v0 = acc[ai][bj][m][0] * rs, v1 = acc[ai][bj][m][1] * rs;
;                     if (ACT == 1) {
; #pragma unroll
;                         for (int j = 0; j < 4; ++j) { v0[j] = gelu_tanh(v0[j]); v1[j] = gelu_tanh(v1[j]); } }
;                     u32x4 w; w.x = cvt_pk_bf16(v0[0], v0[1]); w.y = cvt_pk_bf16(v0[2], v0[3]); w.z = cvt_pk_bf16(v1[0], v1[1]); w.w = cvt_pk_bf16(v1[2], v1[3]);
;                     *(u32x4*)(rowp + bj * HALF) = w; } }
	v_pk_mul_f32 v[148:149], v[148:149], s[100:101]
	v_pk_mul_f32 v[150:151], v[150:151], s[100:101]
	v_pk_mul_f32 v[144:145], v[144:145], v[166:167]
	v_pk_mul_f32 v[146:147], v[146:147], v[166:167]
	v_pk_mul_f32 v[148:149], v[148:149], v[166:167]
	v_pk_mul_f32 v[150:151], v[150:151], v[166:167]
	v_exp_f32_e32 v144, v144
	v_exp_f32_e32 v145, v145
	v_exp_f32_e32 v146, v146
	v_exp_f32_e32 v147, v147
	v_exp_f32_e32 v148, v148
	v_exp_f32_e32 v149, v149
	v_exp_f32_e32 v150, v150
	v_exp_f32_e32 v151, v151
	v_add_f32_e32 v144, 1.0, v144
	v_add_f32_e32 v145, 1.0, v145
	v_add_f32_e32 v146, 1.0, v146
	v_add_f32_e32 v147, 1.0, v147
	v_add_f32_e32 v148, 1.0, v148
	v_add_f32_e32 v149, 1.0, v149
	v_add_f32_e32 v150, 1.0, v150
	v_add_f32_e32 v151, 1.0, v151
	v_rcp_f32_e32 v144, v144
	v_rcp_f32_e32 v145, v145
	v_rcp_f32_e32 v146, v146
	v_rcp_f32_e32 v147, v147
	v_rcp_f32_e32 v148, v148
	v_rcp_f32_e32 v149, v149
	v_rcp_f32_e32 v150, v150
	v_rcp_f32_e32 v151, v151
	v_nop
	v_pk_mul_f32 v[12:13], v[12:13], v[144:145]
	v_pk_mul_f32 v[14:15], v[14:15], v[146:147]
	v_pk_mul_f32 v[8:9], v[8:9], v[148:149]
	v_pk_mul_f32 v[10:11], v[10:11], v[150:151]
	v_cvt_pk_bf16_f32 v12, v12, v13
	v_cvt_pk_bf16_f32 v13, v14, v15
	v_cvt_pk_bf16_f32 v14, v8, v9
	v_cvt_pk_bf16_f32 v15, v10, v11
	global_store_dwordx4 v[142:143], v[12:15], off
	v_pk_mul_f32 v[4:5], v[4:5], v[164:165] op_sel:[0,1]
	v_pk_mul_f32 v[6:7], v[6:7], v[164:165] op_sel:[0,1]
	v_pk_mul_f32 v[0:1], v[0:1], v[164:165] op_sel:[0,1]
	v_pk_mul_f32 v[2:3], v[2:3], v[164:165] op_sel:[0,1]
	v_pk_mul_f32 v[144:145], v[4:5], s[98:99]
	v_pk_mul_f32 v[146:147], v[6:7], s[98:99]
	v_pk_mul_f32 v[148:149], v[0:1], s[98:99]
	v_pk_mul_f32 v[150:151], v[2:3], s[98:99]
	v_pk_mul_f32 v[144:145], v[4:5], v[144:145]
	v_pk_mul_f32 v[146:147], v[6:7], v[146:147]
	v_pk_mul_f32 v[148:149], v[0:1], v[148:149]
	v_pk_mul_f32 v[150:151], v[2:3], v[150:151]
	v_pk_fma_f32 v[144:145], v[4:5], v[144:145], v[4:5]
	v_pk_fma_f32 v[146:147], v[6:7], v[146:147], v[6:7]
	v_pk_fma_f32 v[148:149], v[0:1], v[148:149], v[0:1]
	v_pk_fma_f32 v[150:151], v[2:3], v[150:151], v[2:3]
	v_pk_mul_f32 v[144:145], v[144:145], s[100:101]
	v_pk_mul_f32 v[146:147], v[146:147], s[100:101]
	v_pk_mul_f32 v[148:149], v[148:149], s[100:101]
	v_pk_mul_f32 v[150:151], v[150:151], s[100:101]
	v_pk_mul_f32 v[144:145], v[144:145], v[166:167]
	v_pk_mul_f32 v[146:147], v[146:147], v[166:167]
	v_pk_mul_f32 v[148:149], v[148:149], v[166:167]
	v_pk_mul_f32 v[150:151], v[150:151], v[166:167]
	v_exp_f32_e32 v144, v144
	v_exp_f32_e32 v145, v145
	v_exp_f32_e32 v146, v146
	v_exp_f32_e32 v147, v147
	v_exp_f32_e32 v148, v148
	v_exp_f32_e32 v149, v149
	v_exp_f32_e32 v150, v150
	v_exp_f32_e32 v151, v151
	v_add_f32_e32 v144, 1.0, v144
	v_add_f32_e32 v145, 1.0, v145
	v_add_f32_e32 v146, 1.0, v146
	v_add_f32_e32 v147, 1.0, v147
	v_add_f32_e32 v148, 1.0, v148
	v_add_f32_e32 v149, 1.0, v149
	v_add_f32_e32 v150, 1.0, v150
	v_add_f32_e32 v151, 1.0, v151
	v_rcp_f32_e32 v144, v144
	v_rcp_f32_e32 v145, v145
	v_rcp_f32_e32 v146, v146
	v_rcp_f32_e32 v147, v147
	v_rcp_f32_e32 v148, v148
	v_rcp_f32_e32 v149, v149
	v_rcp_f32_e32 v150, v150
	v_rcp_f32_e32 v151, v151
	v_nop
	v_pk_mul_f32 v[4:5], v[4:5], v[144:145]
	v_pk_mul_f32 v[6:7], v[6:7], v[146:147]
	v_pk_mul_f32 v[0:1], v[0:1], v[148:149]
	v_pk_mul_f32 v[2:3], v[2:3], v[150:151]
	v_cvt_pk_bf16_f32 v4, v4, v5
	v_cvt_pk_bf16_f32 v5, v6, v7
	v_cvt_pk_bf16_f32 v6, v0, v1
	v_cvt_pk_bf16_f32 v7, v2, v3
	global_store_dwordx4 v[142:143], v[4:7], off offset:256
	s_mov_b64 s[10:11], -1
	s_and_b64 vcc, exec, s[8:9]
	s_cbranch_vccnz .LBB0_322
	s_andn2_b64 vcc, exec, s[40:41]
	s_cbranch_vccnz .LBB0_321
	s_barrier
	s_branch .LBB0_321
